# v027 helpers2 + attention row-max canonicalize removal + row-sum split into 4 independent f32 add chains
# speedup vs baseline: 1.0069x; 1.0064x over previous
.LBB0_450:
	s_add_u32 s34, s46, s22
	s_addc_u32 s35, s47, s23
	s_mov_b32 m0, s42
	s_add_u32 s98, s34, s24
	s_addc_u32 s99, s35, s25
	global_load_lds_dwordx4 v203, s[98:99]
	s_mov_b32 m0, s43
	s_add_i32 s4, s41, s50
	global_load_lds_dwordx4 v204, s[98:99]
	s_mov_b32 m0, s48
	s_nop 0
	global_load_lds_dwordx4 v205, s[98:99]
	s_add_u32 s58, s1, s22
	s_addc_u32 s59, s45, s23
	s_mov_b32 m0, s4
	s_mov_b32 s51, s49
	s_add_u32 s100, s58, s26
	s_addc_u32 s101, s59, s27
	global_load_lds_dwordx4 v206, s[100:101]
	s_add_i32 m0, s4, 0x2000
	s_mov_b32 s49, s68
	global_load_lds_dwordx4 v207, s[100:101]
	ds_read_b128 v[64:67], v208 offset:49152
	ds_read_b128 v[68:71], v208 offset:61440
	ds_read_b128 v[222:225], v209 offset:49152
	ds_read_b128 v[226:229], v209 offset:61440
	ds_read_b128 v[230:233], v210 offset:49152
	ds_read_b128 v[234:237], v210 offset:61440
	s_add_i32 s57, 0, 0x12000
	s_waitcnt lgkmcnt(4)
	v_mfma_f32_32x32x16_bf16 v[80:95], v[64:67], v[140:143], 0
	v_exp_f32_e32 v200, v144
	v_mfma_f32_32x32x16_bf16 v[64:79], v[68:71], v[140:143], 0
	v_add_f32_e32 v238, v186, v188
	ds_read_b128 v[214:217], v211 offset:49152
	ds_read_b128 v[218:221], v211 offset:61440
	s_waitcnt lgkmcnt(4)
	v_mfma_f32_32x32x16_bf16 v[80:95], v[222:225], v[136:139], v[80:95]
	v_add_f32_e32 v239, v189, v191
	v_add_f32_e32 v240, v187, v184
	v_add_f32_e32 v241, v190, v185
	v_mfma_f32_32x32x16_bf16 v[64:79], v[226:229], v[136:139], v[64:79]
	v_add_f32_e32 v238, v180, v238
	v_add_f32_e32 v239, v182, v239
	v_add_f32_e32 v240, v181, v240
	ds_read_b128 v[222:225], v208 offset:49280
	ds_read_b128 v[226:229], v208 offset:61568
	s_waitcnt lgkmcnt(4)
	v_mfma_f32_32x32x16_bf16 v[80:95], v[230:233], v[132:135], v[80:95]
	v_add_f32_e32 v241, v183, v241
	v_add_f32_e32 v238, v176, v238
	v_add_f32_e32 v239, v178, v239
	v_mfma_f32_32x32x16_bf16 v[64:79], v[234:237], v[132:135], v[64:79]
	v_exp_f32_e32 v162, v162
	v_add_f32_e32 v240, v177, v240
	v_exp_f32_e32 v163, v163
	v_add_f32_e32 v241, v179, v241
	ds_read_b128 v[230:233], v209 offset:49280
	ds_read_b128 v[234:237], v209 offset:61568
	s_waitcnt lgkmcnt(4)
	v_mfma_f32_32x32x16_bf16 v[80:95], v[214:217], v[128:131], v[80:95]
	v_exp_f32_e32 v201, v145
	v_exp_f32_e32 v148, v164
	v_exp_f32_e32 v164, v165
	v_mfma_f32_32x32x16_bf16 v[64:79], v[218:221], v[128:131], v[64:79]
	v_exp_f32_e32 v165, v158
	v_add_f32_e32 v238, v148, v238
	v_add_f32_e32 v239, v164, v239
	ds_read_b128 v[214:217], v210 offset:49280
	ds_read_b128 v[218:221], v210 offset:61568
	s_waitcnt lgkmcnt(4)
	v_mfma_f32_32x32x16_bf16 v[80:95], v[222:225], v[124:127], v[80:95]
	v_add_f32_e32 v240, v162, v240
	v_add_f32_e32 v241, v163, v241
	v_add_f32_e32 v238, v165, v238
	v_mfma_f32_32x32x16_bf16 v[64:79], v[226:229], v[124:127], v[64:79]
	v_exp_f32_e32 v175, v159
	s_nop 0
	v_add_f32_e32 v239, v175, v239
	ds_read_b128 v[222:225], v211 offset:49280
	ds_read_b128 v[226:229], v211 offset:61568
	s_waitcnt lgkmcnt(4)
	v_mfma_f32_32x32x16_bf16 v[80:95], v[230:233], v[120:123], v[80:95]
	v_exp_f32_e32 v192, v154
	v_exp_f32_e32 v193, v155
	v_exp_f32_e32 v194, v146
	v_mfma_f32_32x32x16_bf16 v[64:79], v[234:237], v[120:123], v[64:79]
	v_exp_f32_e32 v195, v147
	v_add_f32_e32 v240, v192, v240
	v_add_f32_e32 v241, v193, v241
	v_add_f32_e32 v238, v194, v238
	ds_read_b128 v[230:233], v208 offset:49408
	ds_read_b128 v[234:237], v208 offset:61696
	s_waitcnt lgkmcnt(4)
	v_mfma_f32_32x32x16_bf16 v[80:95], v[214:217], v[116:119], v[80:95]
	v_exp_f32_e32 v196, v160
	v_exp_f32_e32 v197, v161
	v_exp_f32_e32 v198, v156
	v_mfma_f32_32x32x16_bf16 v[64:79], v[218:221], v[116:119], v[64:79]
	v_exp_f32_e32 v199, v157
	v_add_f32_e32 v239, v195, v239
	v_add_f32_e32 v240, v196, v240
	ds_read_b128 v[214:217], v209 offset:49408
	ds_read_b128 v[218:221], v209 offset:61696
	s_waitcnt lgkmcnt(4)
	v_mfma_f32_32x32x16_bf16 v[80:95], v[222:225], v[112:115], v[80:95]
	v_add_f32_e32 v241, v197, v241
	v_add_f32_e32 v238, v198, v238
	v_add_f32_e32 v239, v199, v239
	v_mfma_f32_32x32x16_bf16 v[64:79], v[226:229], v[112:115], v[64:79]
	v_add_f32_e32 v240, v200, v240
	v_add_f32_e32 v241, v201, v241
	v_add_f32_e32 v238, v238, v239
	v_add_f32_e32 v240, v240, v241
	v_add_f32_e32 v173, v238, v240
	v_mov_b32_e32 v174, v173
	ds_read_b128 v[222:225], v210 offset:49408
	ds_read_b128 v[226:229], v210 offset:61696
	s_waitcnt lgkmcnt(4)
	v_mfma_f32_32x32x16_bf16 v[80:95], v[230:233], v[108:111], v[80:95]
	v_cvt_pk_bf16_f32 v144, v186, v189
	v_cvt_pk_bf16_f32 v145, v187, v190
	v_cvt_pk_bf16_f32 v146, v188, v191
	v_mfma_f32_32x32x16_bf16 v[64:79], v[234:237], v[108:111], v[64:79]
	s_nop 1
	v_permlane32_swap_b32_e32 v173, v174
	v_cvt_pk_bf16_f32 v147, v184, v185
	v_permlane32_swap_b32_e32 v144, v146
	ds_read_b128 v[230:233], v211 offset:49408
	ds_read_b128 v[234:237], v211 offset:61696
	s_waitcnt lgkmcnt(4)
	v_mfma_f32_32x32x16_bf16 v[80:95], v[214:217], v[104:107], v[80:95]
	v_cvt_pk_bf16_f32 v154, v180, v182
	v_cvt_pk_bf16_f32 v155, v181, v183
	v_cvt_pk_bf16_f32 v156, v176, v178
	v_mfma_f32_32x32x16_bf16 v[64:79], v[218:221], v[104:107], v[64:79]
	v_cvt_pk_bf16_f32 v157, v177, v179
	v_cvt_pk_bf16_f32 v158, v148, v164
	v_cvt_pk_bf16_f32 v159, v162, v163
	s_waitcnt lgkmcnt(2)
	v_mfma_f32_32x32x16_bf16 v[80:95], v[222:225], v[100:103], v[80:95]
	v_cvt_pk_bf16_f32 v160, v165, v175
	v_cvt_pk_bf16_f32 v161, v192, v193
	v_cvt_pk_bf16_f32 v162, v194, v195
	v_mfma_f32_32x32x16_bf16 v[64:79], v[226:229], v[100:103], v[64:79]
	v_cvt_pk_bf16_f32 v163, v196, v197
	v_cvt_pk_bf16_f32 v164, v198, v199
	v_cvt_pk_bf16_f32 v165, v200, v201
	s_waitcnt lgkmcnt(0)
	v_mfma_f32_32x32x16_bf16 v[80:95], v[230:233], v[96:99], v[80:95]
	v_permlane32_swap_b32_e32 v145, v147
	v_permlane32_swap_b32_e32 v154, v156
	v_permlane32_swap_b32_e32 v155, v157
	v_mfma_f32_32x32x16_bf16 v[64:79], v[234:237], v[96:99], v[64:79]
	v_permlane32_swap_b32_e32 v158, v160
	v_permlane32_swap_b32_e32 v159, v161
	v_permlane32_swap_b32_e32 v162, v164
	v_permlane32_swap_b32_e32 v163, v165
	s_cmp_lg_u32 0, -1
	s_cselect_b32 s4, 0, 0
	s_add_i32 s44, s68, s4
	v_add_u32_e32 v148, s44, v212
	ds_read_b64_tr_b16 v[176:177], v148 offset:0
	ds_read_b64_tr_b16 v[178:179], v148 offset:0x800
	ds_read_b64_tr_b16 v[180:181], v148 offset:0x1000
	ds_read_b64_tr_b16 v[182:183], v148 offset:0x1800
	ds_read_b64_tr_b16 v[184:185], v148 offset:0x2000
	ds_read_b64_tr_b16 v[186:187], v148 offset:0x2800
	ds_read_b64_tr_b16 v[188:189], v148 offset:0x3000
	ds_read_b64_tr_b16 v[190:191], v148 offset:0x3800
	s_waitcnt lgkmcnt(0)
	s_nop 0
	v_mfma_f32_32x32x16_bf16 v[0:15], v[144:147], v[176:179], v[0:15]
	ds_read_b64_tr_b16 v[176:177], v148 offset:0x200
	ds_read_b64_tr_b16 v[178:179], v148 offset:0xa00
	v_mfma_f32_32x32x16_bf16 v[0:15], v[154:157], v[180:183], v[0:15]
	ds_read_b64_tr_b16 v[180:181], v148 offset:0x1200
	ds_read_b64_tr_b16 v[182:183], v148 offset:0x1a00
	v_mfma_f32_32x32x16_bf16 v[0:15], v[158:161], v[184:187], v[0:15]
	ds_read_b64_tr_b16 v[184:185], v148 offset:0x2200
	ds_read_b64_tr_b16 v[186:187], v148 offset:0x2a00
	v_mfma_f32_32x32x16_bf16 v[0:15], v[162:165], v[188:191], v[0:15]
	ds_read_b64_tr_b16 v[188:189], v148 offset:0x3200
	ds_read_b64_tr_b16 v[190:191], v148 offset:0x3a00
	s_waitcnt lgkmcnt(0)
	v_mfma_f32_32x32x16_bf16 v[48:63], v[144:147], v[176:179], v[48:63]
	ds_read_b64_tr_b16 v[176:177], v148 offset:0x400
	ds_read_b64_tr_b16 v[178:179], v148 offset:0xc00
	v_mfma_f32_32x32x16_bf16 v[48:63], v[154:157], v[180:183], v[48:63]
	ds_read_b64_tr_b16 v[180:181], v148 offset:0x1400
	ds_read_b64_tr_b16 v[182:183], v148 offset:0x1c00
	v_mfma_f32_32x32x16_bf16 v[48:63], v[158:161], v[184:187], v[48:63]
	ds_read_b64_tr_b16 v[184:185], v148 offset:0x2400
	ds_read_b64_tr_b16 v[186:187], v148 offset:0x2c00
	v_mfma_f32_32x32x16_bf16 v[48:63], v[162:165], v[188:191], v[48:63]
	ds_read_b64_tr_b16 v[188:189], v148 offset:0x3400
	ds_read_b64_tr_b16 v[190:191], v148 offset:0x3c00
	s_waitcnt lgkmcnt(0)
	v_mfma_f32_32x32x16_bf16 v[32:47], v[144:147], v[176:179], v[32:47]
	ds_read_b64_tr_b16 v[176:177], v148 offset:0x600
	ds_read_b64_tr_b16 v[178:179], v148 offset:0xe00
	v_mfma_f32_32x32x16_bf16 v[32:47], v[154:157], v[180:183], v[32:47]
	ds_read_b64_tr_b16 v[180:181], v148 offset:0x1600
	ds_read_b64_tr_b16 v[182:183], v148 offset:0x1e00
	v_mfma_f32_32x32x16_bf16 v[32:47], v[158:161], v[184:187], v[32:47]
	ds_read_b64_tr_b16 v[184:185], v148 offset:0x2600
	ds_read_b64_tr_b16 v[186:187], v148 offset:0x2e00
	v_mfma_f32_32x32x16_bf16 v[32:47], v[162:165], v[188:191], v[32:47]
	ds_read_b64_tr_b16 v[188:189], v148 offset:0x3600
	ds_read_b64_tr_b16 v[190:191], v148 offset:0x3e00
	s_waitcnt lgkmcnt(0)
	v_mfma_f32_32x32x16_bf16 v[16:31], v[144:147], v[176:179], v[16:31]
	v_max_f32_e32 v144, v80, v81
	v_max3_f32 v144, v144, v82, v83
	v_max3_f32 v144, v144, v84, v85
	v_max3_f32 v144, v144, v86, v87
	v_max3_f32 v144, v144, v88, v89
	v_max3_f32 v144, v144, v90, v91
	v_max3_f32 v144, v144, v92, v93
	v_mfma_f32_32x32x16_bf16 v[16:31], v[154:157], v[180:183], v[16:31]
	v_max3_f32 v144, v144, v94, v95
	v_max3_f32 v144, v144, v64, v65
	v_max3_f32 v144, v144, v66, v67
	v_max3_f32 v144, v144, v68, v69
	v_max3_f32 v144, v144, v70, v71
	v_max3_f32 v144, v144, v72, v73
	v_max3_f32 v144, v144, v74, v75
	v_max3_f32 v144, v144, v76, v77
	v_mfma_f32_32x32x16_bf16 v[16:31], v[158:161], v[184:187], v[16:31]
	v_max3_f32 v144, v144, v78, v79
	v_mov_b32_e32 v145, v144
	s_nop 1
	v_permlane32_swap_b32_e32 v144, v145
	v_max_f32_e32 v144, v144, v145
	v_sub_f32_e32 v145, v144, v172
	v_cmp_ge_f32_e32 vcc, s37, v145
	v_max_f32_e32 v144, v172, v144
	v_mfma_f32_32x32x16_bf16 v[16:31], v[162:165], v[188:191], v[16:31]
	v_sub_f32_e32 v145, v172, v144
	v_mul_f32_e32 v145, 0x3dd53b94, v145
	v_exp_f32_e32 v145, v145
	s_cmp_eq_u64 vcc, exec
	s_cselect_b64 s[4:5], -1, 0
	s_waitcnt vmcnt(0)
	v_cndmask_b32_e64 v175, v145, 1.0, s[4:5]
	v_cmp_gt_f32_e32 vcc, 1.0, v175
	s_waitcnt vmcnt(0)
	s_barrier
	s_cbranch_vccz .LBB0_454
	s_and_saveexec_b64 s[60:61], s[2:3]
	ds_write_b32 v153, v175 offset:128
	s_or_b64 exec, exec, s[60:61]
	s_waitcnt lgkmcnt(0)
	v_add_u32_e32 v145, v151, v152
	ds_read_b128 v[154:157], v145 offset:224
	ds_read_b128 v[158:161], v145 offset:192
	ds_read_b128 v[162:165], v145 offset:160
	ds_read_b128 v[176:179], v145 offset:128
	s_waitcnt lgkmcnt(3)
	v_pk_mul_f32 v[12:13], v[12:13], v[154:155]
	s_waitcnt lgkmcnt(2)
	v_pk_mul_f32 v[8:9], v[8:9], v[158:159]
	s_waitcnt lgkmcnt(1)
	v_pk_mul_f32 v[4:5], v[4:5], v[162:163]
	v_pk_mul_f32 v[14:15], v[14:15], v[156:157]
	v_pk_mul_f32 v[10:11], v[10:11], v[160:161]
	v_pk_mul_f32 v[6:7], v[6:7], v[164:165]
	s_waitcnt lgkmcnt(0)
	v_pk_mul_f32 v[2:3], v[2:3], v[178:179]
	v_pk_mul_f32 v[0:1], v[0:1], v[176:177]
	v_pk_mul_f32 v[60:61], v[60:61], v[154:155]
	v_pk_mul_f32 v[56:57], v[56:57], v[158:159]
	v_pk_mul_f32 v[52:53], v[52:53], v[162:163]
	v_pk_mul_f32 v[62:63], v[62:63], v[156:157]
	v_pk_mul_f32 v[58:59], v[58:59], v[160:161]
	v_pk_mul_f32 v[54:55], v[54:55], v[164:165]
	v_pk_mul_f32 v[50:51], v[50:51], v[178:179]
	v_pk_mul_f32 v[48:49], v[48:49], v[176:177]
	v_pk_mul_f32 v[44:45], v[44:45], v[154:155]
	v_pk_mul_f32 v[40:41], v[40:41], v[158:159]
	v_pk_mul_f32 v[36:37], v[36:37], v[162:163]
	v_pk_mul_f32 v[46:47], v[46:47], v[156:157]
	v_pk_mul_f32 v[42:43], v[42:43], v[160:161]
	v_pk_mul_f32 v[38:39], v[38:39], v[164:165]
	v_pk_mul_f32 v[34:35], v[34:35], v[178:179]
	v_pk_mul_f32 v[32:33], v[32:33], v[176:177]
	v_pk_mul_f32 v[28:29], v[28:29], v[154:155]
	v_pk_mul_f32 v[24:25], v[24:25], v[158:159]
	v_pk_mul_f32 v[20:21], v[20:21], v[162:163]
	v_pk_mul_f32 v[30:31], v[30:31], v[156:157]
	v_pk_mul_f32 v[26:27], v[26:27], v[160:161]
	v_pk_mul_f32 v[22:23], v[22:23], v[164:165]
	v_pk_mul_f32 v[18:19], v[18:19], v[178:179]
	v_pk_mul_f32 v[16:17], v[16:17], v[176:177]
.LBB0_454:
	v_cndmask_b32_e64 v154, v144, v172, s[4:5]
	v_mul_f32_e32 v176, 0xbdd53b94, v154
	v_fmamk_f32 v187, v66, 0x3dd53b94, v176
	v_fmamk_f32 v185, v64, 0x3dd53b94, v176
	v_fmamk_f32 v186, v65, 0x3dd53b94, v176
	v_fmamk_f32 v188, v67, 0x3dd53b94, v176
	s_cmp_lg_u32 0, -1
	s_cselect_b32 s4, 0, 0
	s_add_i32 s5, s4, s40
	s_add_i32 m0, s5, 0x12000
	v_fmamk_f32 v178, v69, 0x3dd53b94, v176
	s_add_u32 s98, s34, s52
	s_addc_u32 s99, s35, s53
	global_load_lds_dwordx4 v203, s[98:99]
	s_add_i32 m0, s5, 0x14000
	v_fmamk_f32 v179, v70, 0x3dd53b94, v176
	global_load_lds_dwordx4 v204, s[98:99]
	s_add_i32 m0, s5, 0x16000
	v_fmamk_f32 v189, v68, 0x3dd53b94, v176
	global_load_lds_dwordx4 v205, s[98:99]
	v_fmamk_f32 v180, v71, 0x3dd53b94, v176
	s_add_i32 s5, s41, s49
	s_mov_b32 m0, s5
	v_fmamk_f32 v80, v80, 0x3dd53b94, v176
	s_add_u32 s100, s58, s54
	s_addc_u32 s101, s59, s55
	global_load_lds_dwordx4 v206, s[100:101]
	s_add_i32 m0, s5, 0x2000
	v_exp_f32_e32 v144, v80
	global_load_lds_dwordx4 v207, s[100:101]
	v_fmamk_f32 v81, v81, 0x3dd53b94, v176
	v_fmamk_f32 v82, v82, 0x3dd53b94, v176
	v_fmamk_f32 v83, v83, 0x3dd53b94, v176
	v_fmamk_f32 v84, v84, 0x3dd53b94, v176
	v_fmamk_f32 v85, v85, 0x3dd53b94, v176
	v_fmamk_f32 v86, v86, 0x3dd53b94, v176
	v_fmamk_f32 v87, v87, 0x3dd53b94, v176
	v_fmamk_f32 v88, v88, 0x3dd53b94, v176
	v_fmamk_f32 v89, v89, 0x3dd53b94, v176
	v_fmamk_f32 v90, v90, 0x3dd53b94, v176
	v_fmamk_f32 v91, v91, 0x3dd53b94, v176
	v_fmamk_f32 v92, v92, 0x3dd53b94, v176
	v_fmamk_f32 v93, v93, 0x3dd53b94, v176
	v_fmamk_f32 v94, v94, 0x3dd53b94, v176
	v_fmamk_f32 v95, v95, 0x3dd53b94, v176
	v_fmamk_f32 v181, v72, 0x3dd53b94, v176
	v_fmamk_f32 v182, v73, 0x3dd53b94, v176
	v_fmamk_f32 v183, v74, 0x3dd53b94, v176
	v_fmamk_f32 v184, v75, 0x3dd53b94, v176
	v_fmamk_f32 v177, v76, 0x3dd53b94, v176
	v_exp_f32_e32 v172, v81
	v_exp_f32_e32 v145, v82
	v_exp_f32_e32 v165, v83
	v_exp_f32_e32 v146, v84
	v_exp_f32_e32 v164, v85
	v_exp_f32_e32 v147, v86
	v_exp_f32_e32 v163, v87
	v_exp_f32_e32 v160, v88
	v_exp_f32_e32 v162, v89
	v_exp_f32_e32 v159, v90
	v_exp_f32_e32 v161, v91
	v_exp_f32_e32 v156, v92
	v_exp_f32_e32 v158, v93
	v_exp_f32_e32 v155, v94
	v_exp_f32_e32 v157, v95
	v_fmamk_f32 v190, v77, 0x3dd53b94, v176
	v_fmamk_f32 v191, v78, 0x3dd53b94, v176
	v_fmac_f32_e32 v176, 0x3dd53b94, v79
	ds_read_b128 v[64:67], v208 offset:24576
	ds_read_b128 v[68:71], v208 offset:36864
	ds_read_b128 v[222:225], v209 offset:24576
	ds_read_b128 v[226:229], v209 offset:36864
	ds_read_b128 v[230:233], v210 offset:24576
	ds_read_b128 v[234:237], v210 offset:36864
	s_waitcnt lgkmcnt(4)
	v_mfma_f32_32x32x16_bf16 v[80:95], v[64:67], v[140:143], 0
	v_exp_f32_e32 v178, v178
	v_exp_f32_e32 v179, v179
	v_exp_f32_e32 v180, v180
	v_mfma_f32_32x32x16_bf16 v[64:79], v[68:71], v[140:143], 0
	v_exp_f32_e32 v181, v181
	v_exp_f32_e32 v182, v182
	v_exp_f32_e32 v183, v183
	ds_read_b128 v[214:217], v211 offset:24576
	ds_read_b128 v[218:221], v211 offset:36864
	s_waitcnt lgkmcnt(4)
	v_mfma_f32_32x32x16_bf16 v[80:95], v[222:225], v[136:139], v[80:95]
	v_exp_f32_e32 v184, v184
	v_exp_f32_e32 v190, v190
	v_exp_f32_e32 v191, v191
	v_mfma_f32_32x32x16_bf16 v[64:79], v[226:229], v[136:139], v[64:79]
	v_exp_f32_e32 v148, v185
	v_exp_f32_e32 v185, v186
	v_exp_f32_e32 v186, v187
	ds_read_b128 v[222:225], v208 offset:24704
	ds_read_b128 v[226:229], v208 offset:36992
	s_waitcnt lgkmcnt(4)
	v_mfma_f32_32x32x16_bf16 v[80:95], v[230:233], v[132:135], v[80:95]
	v_exp_f32_e32 v187, v188
	v_exp_f32_e32 v188, v189
	v_exp_f32_e32 v189, v177
	v_mfma_f32_32x32x16_bf16 v[64:79], v[234:237], v[132:135], v[64:79]
	v_exp_f32_e32 v194, v176
	ds_read_b128 v[230:233], v209 offset:24704
	ds_read_b128 v[234:237], v209 offset:36992
	s_waitcnt lgkmcnt(4)
	v_mfma_f32_32x32x16_bf16 v[80:95], v[214:217], v[128:131], v[80:95]
	v_add_f32_e32 v238, v144, v146
	v_mfma_f32_32x32x16_bf16 v[64:79], v[218:221], v[128:131], v[64:79]
	v_add_f32_e32 v239, v172, v164
	v_add_f32_e32 v240, v145, v147
	v_add_f32_e32 v241, v165, v163
	v_add_f32_e32 v238, v160, v238
	ds_read_b128 v[214:217], v210 offset:24704
	ds_read_b128 v[218:221], v210 offset:36992
	s_waitcnt lgkmcnt(4)
	v_mfma_f32_32x32x16_bf16 v[80:95], v[222:225], v[124:127], v[80:95]
	v_add_f32_e32 v239, v162, v239
	v_add_f32_e32 v240, v159, v240
	v_add_f32_e32 v241, v161, v241
	v_mfma_f32_32x32x16_bf16 v[64:79], v[226:229], v[124:127], v[64:79]
	v_add_f32_e32 v238, v156, v238
	v_add_f32_e32 v239, v158, v239
	v_add_f32_e32 v240, v155, v240
	ds_read_b128 v[222:225], v211 offset:24704
	ds_read_b128 v[226:229], v211 offset:36992
	s_waitcnt lgkmcnt(4)
	v_mfma_f32_32x32x16_bf16 v[80:95], v[230:233], v[120:123], v[80:95]
	v_add_f32_e32 v241, v157, v241
	v_add_f32_e32 v238, v148, v238
	v_add_f32_e32 v239, v185, v239
	v_mfma_f32_32x32x16_bf16 v[64:79], v[234:237], v[120:123], v[64:79]
	v_add_f32_e32 v240, v186, v240
	v_add_f32_e32 v241, v187, v241
	v_add_f32_e32 v238, v188, v238
	ds_read_b128 v[230:233], v208 offset:24832
	ds_read_b128 v[234:237], v208 offset:37120
	s_waitcnt lgkmcnt(4)
	v_mfma_f32_32x32x16_bf16 v[80:95], v[214:217], v[116:119], v[80:95]
	v_add_f32_e32 v239, v178, v239
	v_add_f32_e32 v240, v179, v240
	v_add_f32_e32 v241, v180, v241
	v_mfma_f32_32x32x16_bf16 v[64:79], v[218:221], v[116:119], v[64:79]
	v_add_f32_e32 v238, v181, v238
	v_add_f32_e32 v239, v182, v239
	v_add_f32_e32 v240, v183, v240
	ds_read_b128 v[214:217], v209 offset:24832
	ds_read_b128 v[218:221], v209 offset:37120
	s_waitcnt lgkmcnt(4)
	v_mfma_f32_32x32x16_bf16 v[80:95], v[222:225], v[112:115], v[80:95]
	v_add_f32_e32 v241, v184, v241
	v_add_f32_e32 v238, v189, v238
	v_add_f32_e32 v239, v190, v239
	v_mfma_f32_32x32x16_bf16 v[64:79], v[226:229], v[112:115], v[64:79]
	v_add_f32_e32 v240, v191, v240
	v_add_f32_e32 v241, v194, v241
	v_add_f32_e32 v238, v238, v239
	v_add_f32_e32 v240, v240, v241
	v_add_f32_e32 v192, v238, v240
	v_mov_b32_e32 v193, v192
	v_cvt_pk_bf16_f32 v144, v144, v172
	ds_read_b128 v[222:225], v210 offset:24832
	ds_read_b128 v[226:229], v210 offset:37120
	s_waitcnt lgkmcnt(4)
	v_mfma_f32_32x32x16_bf16 v[80:95], v[230:233], v[108:111], v[80:95]
	v_cvt_pk_bf16_f32 v145, v145, v165
	v_cvt_pk_bf16_f32 v146, v146, v164
	s_nop 1
	v_mfma_f32_32x32x16_bf16 v[64:79], v[234:237], v[108:111], v[64:79]
	v_permlane32_swap_b32_e32 v192, v193
	v_cvt_pk_bf16_f32 v147, v147, v163
	v_permlane32_swap_b32_e32 v144, v146
	ds_read_b128 v[230:233], v211 offset:24832
	ds_read_b128 v[234:237], v211 offset:37120
	s_waitcnt lgkmcnt(4)
	v_mfma_f32_32x32x16_bf16 v[80:95], v[214:217], v[104:107], v[80:95]
	v_cvt_pk_bf16_f32 v160, v160, v162
	v_cvt_pk_bf16_f32 v161, v159, v161
	v_cvt_pk_bf16_f32 v162, v156, v158
	v_mfma_f32_32x32x16_bf16 v[64:79], v[218:221], v[104:107], v[64:79]
	v_cvt_pk_bf16_f32 v163, v155, v157
	v_cvt_pk_bf16_f32 v156, v148, v185
	v_cvt_pk_bf16_f32 v157, v186, v187
	s_waitcnt lgkmcnt(2)
	v_mfma_f32_32x32x16_bf16 v[80:95], v[222:225], v[100:103], v[80:95]
	v_cvt_pk_bf16_f32 v158, v188, v178
	v_cvt_pk_bf16_f32 v159, v179, v180
	v_cvt_pk_bf16_f32 v176, v181, v182
	v_mfma_f32_32x32x16_bf16 v[64:79], v[226:229], v[100:103], v[64:79]
	v_cvt_pk_bf16_f32 v177, v183, v184
	v_cvt_pk_bf16_f32 v178, v189, v190
	v_cvt_pk_bf16_f32 v179, v191, v194
	s_waitcnt lgkmcnt(0)
	v_mfma_f32_32x32x16_bf16 v[80:95], v[230:233], v[96:99], v[80:95]
	v_permlane32_swap_b32_e32 v145, v147
	v_permlane32_swap_b32_e32 v160, v162
	v_permlane32_swap_b32_e32 v161, v163
	v_mfma_f32_32x32x16_bf16 v[64:79], v[234:237], v[96:99], v[64:79]
	v_permlane32_swap_b32_e32 v156, v158
	v_permlane32_swap_b32_e32 v157, v159
	v_permlane32_swap_b32_e32 v176, v178
	v_permlane32_swap_b32_e32 v177, v179
	s_add_i32 s4, s51, s4
	v_add_u32_e32 v148, s4, v212
	ds_read_b64_tr_b16 v[180:181], v148 offset:0
	ds_read_b64_tr_b16 v[182:183], v148 offset:0x800
	ds_read_b64_tr_b16 v[184:185], v148 offset:0x1000
	ds_read_b64_tr_b16 v[186:187], v148 offset:0x1800
	ds_read_b64_tr_b16 v[188:189], v148 offset:0x2000
	ds_read_b64_tr_b16 v[190:191], v148 offset:0x2800
	ds_read_b64_tr_b16 v[194:195], v148 offset:0x3000
	ds_read_b64_tr_b16 v[196:197], v148 offset:0x3800
	s_waitcnt lgkmcnt(0)
	s_nop 0
	v_mfma_f32_32x32x16_bf16 v[0:15], v[144:147], v[180:183], v[0:15]
	ds_read_b64_tr_b16 v[180:181], v148 offset:0x200
	ds_read_b64_tr_b16 v[182:183], v148 offset:0xa00
	v_mfma_f32_32x32x16_bf16 v[0:15], v[160:163], v[184:187], v[0:15]
	ds_read_b64_tr_b16 v[184:185], v148 offset:0x1200
	ds_read_b64_tr_b16 v[186:187], v148 offset:0x1a00
	v_mfma_f32_32x32x16_bf16 v[0:15], v[156:159], v[188:191], v[0:15]
	ds_read_b64_tr_b16 v[188:189], v148 offset:0x2200
	ds_read_b64_tr_b16 v[190:191], v148 offset:0x2a00
	v_mfma_f32_32x32x16_bf16 v[0:15], v[176:179], v[194:197], v[0:15]
	ds_read_b64_tr_b16 v[194:195], v148 offset:0x3200
	ds_read_b64_tr_b16 v[196:197], v148 offset:0x3a00
	s_waitcnt lgkmcnt(0)
	v_mfma_f32_32x32x16_bf16 v[48:63], v[144:147], v[180:183], v[48:63]
	ds_read_b64_tr_b16 v[180:181], v148 offset:0x400
	ds_read_b64_tr_b16 v[182:183], v148 offset:0xc00
	v_mfma_f32_32x32x16_bf16 v[48:63], v[160:163], v[184:187], v[48:63]
	ds_read_b64_tr_b16 v[184:185], v148 offset:0x1400
	ds_read_b64_tr_b16 v[186:187], v148 offset:0x1c00
	v_mfma_f32_32x32x16_bf16 v[48:63], v[156:159], v[188:191], v[48:63]
	ds_read_b64_tr_b16 v[188:189], v148 offset:0x2400
	ds_read_b64_tr_b16 v[190:191], v148 offset:0x2c00
	v_mfma_f32_32x32x16_bf16 v[48:63], v[176:179], v[194:197], v[48:63]
	ds_read_b64_tr_b16 v[194:195], v148 offset:0x3400
	ds_read_b64_tr_b16 v[196:197], v148 offset:0x3c00
	s_waitcnt lgkmcnt(0)
	v_mfma_f32_32x32x16_bf16 v[32:47], v[144:147], v[180:183], v[32:47]
	ds_read_b64_tr_b16 v[180:181], v148 offset:0x600
	ds_read_b64_tr_b16 v[182:183], v148 offset:0xe00
	v_mfma_f32_32x32x16_bf16 v[32:47], v[160:163], v[184:187], v[32:47]
	ds_read_b64_tr_b16 v[184:185], v148 offset:0x1600
	ds_read_b64_tr_b16 v[186:187], v148 offset:0x1e00
	v_mfma_f32_32x32x16_bf16 v[32:47], v[156:159], v[188:191], v[32:47]
	ds_read_b64_tr_b16 v[188:189], v148 offset:0x2600
	ds_read_b64_tr_b16 v[190:191], v148 offset:0x2e00
	v_mfma_f32_32x32x16_bf16 v[32:47], v[176:179], v[194:197], v[32:47]
	ds_read_b64_tr_b16 v[194:195], v148 offset:0x3600
	ds_read_b64_tr_b16 v[196:197], v148 offset:0x3e00
	s_waitcnt lgkmcnt(0)
	v_mfma_f32_32x32x16_bf16 v[16:31], v[144:147], v[180:183], v[16:31]
	v_max_f32_e32 v144, v80, v81
	v_max3_f32 v144, v144, v82, v83
	v_max3_f32 v144, v144, v84, v85
	v_max3_f32 v144, v144, v86, v87
	v_max3_f32 v144, v144, v88, v89
	v_max3_f32 v144, v144, v90, v91
	v_max3_f32 v144, v144, v92, v93
	v_mfma_f32_32x32x16_bf16 v[16:31], v[160:163], v[184:187], v[16:31]
	v_max3_f32 v144, v144, v94, v95
	v_max3_f32 v144, v144, v64, v65
	v_max3_f32 v144, v144, v66, v67
	v_max3_f32 v144, v144, v68, v69
	v_max3_f32 v144, v144, v70, v71
	v_max3_f32 v144, v144, v72, v73
	v_max3_f32 v144, v144, v74, v75
	v_max3_f32 v144, v144, v76, v77
	v_mfma_f32_32x32x16_bf16 v[16:31], v[156:159], v[188:191], v[16:31]
	v_max3_f32 v144, v144, v78, v79
	v_mov_b32_e32 v145, v144
	s_nop 1
	v_permlane32_swap_b32_e32 v144, v145
	v_max_f32_e32 v144, v144, v145
	v_sub_f32_e32 v145, v144, v154
	v_cmp_ge_f32_e32 vcc, s37, v145
	v_max_f32_e32 v144, v154, v144
	v_mfma_f32_32x32x16_bf16 v[16:31], v[176:179], v[194:197], v[16:31]
	v_sub_f32_e32 v145, v154, v144
	v_mul_f32_e32 v145, 0x3dd53b94, v145
	v_exp_f32_e32 v145, v145
	s_cmp_eq_u64 vcc, exec
	s_cselect_b64 s[4:5], -1, 0
	s_waitcnt vmcnt(0)
	v_cndmask_b32_e64 v148, v145, 1.0, s[4:5]
	v_cmp_gt_f32_e32 vcc, 1.0, v148
	s_waitcnt vmcnt(0)
	s_barrier
	s_cbranch_vccz .LBB0_458
	s_and_saveexec_b64 s[34:35], s[2:3]
	ds_write_b32 v153, v148 offset:128
	s_or_b64 exec, exec, s[34:35]
	s_waitcnt lgkmcnt(0)
	v_add_u32_e32 v145, v151, v152
	ds_read_b128 v[156:159], v145 offset:224
	ds_read_b128 v[160:163], v145 offset:192
	ds_read_b128 v[176:179], v145 offset:160
	ds_read_b128 v[180:183], v145 offset:128
	s_waitcnt lgkmcnt(3)
	v_pk_mul_f32 v[12:13], v[12:13], v[156:157]
	s_waitcnt lgkmcnt(2)
	v_pk_mul_f32 v[8:9], v[8:9], v[160:161]
	s_waitcnt lgkmcnt(1)
	v_pk_mul_f32 v[4:5], v[4:5], v[176:177]
	v_pk_mul_f32 v[14:15], v[14:15], v[158:159]
	v_pk_mul_f32 v[10:11], v[10:11], v[162:163]
	v_pk_mul_f32 v[6:7], v[6:7], v[178:179]
	s_waitcnt lgkmcnt(0)
	v_pk_mul_f32 v[2:3], v[2:3], v[182:183]
	v_pk_mul_f32 v[0:1], v[0:1], v[180:181]
	v_pk_mul_f32 v[60:61], v[60:61], v[156:157]
	v_pk_mul_f32 v[56:57], v[56:57], v[160:161]
	v_pk_mul_f32 v[52:53], v[52:53], v[176:177]
	v_pk_mul_f32 v[62:63], v[62:63], v[158:159]
	v_pk_mul_f32 v[58:59], v[58:59], v[162:163]
	v_pk_mul_f32 v[54:55], v[54:55], v[178:179]
	v_pk_mul_f32 v[50:51], v[50:51], v[182:183]
	v_pk_mul_f32 v[48:49], v[48:49], v[180:181]
	v_pk_mul_f32 v[44:45], v[44:45], v[156:157]
	v_pk_mul_f32 v[40:41], v[40:41], v[160:161]
	v_pk_mul_f32 v[36:37], v[36:37], v[176:177]
	v_pk_mul_f32 v[46:47], v[46:47], v[158:159]
	v_pk_mul_f32 v[42:43], v[42:43], v[162:163]
	v_pk_mul_f32 v[38:39], v[38:39], v[178:179]
	v_pk_mul_f32 v[34:35], v[34:35], v[182:183]
	v_pk_mul_f32 v[32:33], v[32:33], v[180:181]
	v_pk_mul_f32 v[28:29], v[28:29], v[156:157]
	v_pk_mul_f32 v[24:25], v[24:25], v[160:161]
	v_pk_mul_f32 v[20:21], v[20:21], v[176:177]
	v_pk_mul_f32 v[30:31], v[30:31], v[158:159]
	v_pk_mul_f32 v[26:27], v[26:27], v[162:163]
	v_pk_mul_f32 v[22:23], v[22:23], v[178:179]
	v_pk_mul_f32 v[18:19], v[18:19], v[182:183]
	v_pk_mul_f32 v[16:17], v[16:17], v[180:181]

.LBB0_1098:
	s_add_u32 s34, s43, s16
	s_addc_u32 s35, s44, s17
	s_mov_b32 m0, s76
	s_add_u32 s98, s34, s20
	s_addc_u32 s99, s35, s21
	global_load_lds_dwordx4 v240, s[98:99]
	s_mov_b32 m0, s77
	s_nop 0
	global_load_lds_dwordx4 v241, s[98:99]
	s_mov_b32 m0, s45
	s_nop 0
	global_load_lds_dwordx4 v242, s[98:99]
	s_add_i32 s4, s1, s47
	s_add_u32 s38, s41, s16
	s_addc_u32 s39, s42, s17
	s_mov_b32 m0, s4
	s_mov_b32 s48, s46
	s_add_u32 s100, s38, s22
	s_addc_u32 s101, s39, s23
	global_load_lds_dwordx4 v243, s[100:101]
	s_add_i32 m0, s4, 0x2000
	s_mov_b32 s46, s36
	global_load_lds_dwordx4 v244, s[100:101]
	ds_read_b128 v[64:67], v246 offset:49152
	ds_read_b128 v[68:71], v246 offset:61440
	ds_read_b128 v[232:235], v247 offset:49152
	ds_read_b128 v[236:239], v247 offset:61440
	ds_read_b128 v[200:203], v248 offset:49152
	ds_read_b128 v[204:207], v248 offset:61440
	s_add_i32 s49, 0, 0x12000
	s_waitcnt lgkmcnt(4)
	v_mfma_f32_32x32x16_bf16 v[80:95], v[64:67], v[140:143], 0
	v_exp_f32_e32 v160, v160
	v_exp_f32_e32 v161, v161
	v_exp_f32_e32 v164, v164
	v_mfma_f32_32x32x16_bf16 v[64:79], v[68:71], v[140:143], 0
	v_exp_f32_e32 v165, v165
	v_exp_f32_e32 v175, v157
	v_exp_f32_e32 v144, v162
	ds_read_b128 v[216:219], v249 offset:49152
	ds_read_b128 v[220:223], v249 offset:61440
	s_waitcnt lgkmcnt(4)
	v_mfma_f32_32x32x16_bf16 v[80:95], v[232:235], v[136:139], v[80:95]
	v_exp_f32_e32 v162, v163
	v_exp_f32_e32 v163, v156
	v_exp_f32_e32 v214, v150
	v_mfma_f32_32x32x16_bf16 v[64:79], v[236:239], v[136:139], v[64:79]
	ds_read_b128 v[232:235], v246 offset:49280
	ds_read_b128 v[236:239], v246 offset:61568
	s_waitcnt lgkmcnt(4)
	v_mfma_f32_32x32x16_bf16 v[80:95], v[200:203], v[132:135], v[80:95]
	v_add_f32_e32 v224, v185, v187
	v_add_f32_e32 v225, v189, v191
	v_mfma_f32_32x32x16_bf16 v[64:79], v[204:207], v[132:135], v[64:79]
	v_add_f32_e32 v226, v186, v184
	v_add_f32_e32 v227, v190, v188
	v_add_f32_e32 v224, v178, v224
	ds_read_b128 v[200:203], v247 offset:49280
	ds_read_b128 v[204:207], v247 offset:61568
	s_waitcnt lgkmcnt(4)
	v_mfma_f32_32x32x16_bf16 v[80:95], v[216:219], v[128:131], v[80:95]
	v_add_f32_e32 v225, v182, v225
	v_add_f32_e32 v226, v179, v226
	v_add_f32_e32 v227, v183, v227
	v_mfma_f32_32x32x16_bf16 v[64:79], v[220:223], v[128:131], v[64:79]
	v_add_f32_e32 v224, v176, v224
	v_add_f32_e32 v225, v180, v225
	v_add_f32_e32 v226, v177, v226
	v_add_f32_e32 v227, v181, v227
	ds_read_b128 v[216:219], v248 offset:49280
	ds_read_b128 v[220:223], v248 offset:61568
	s_waitcnt lgkmcnt(4)
	v_mfma_f32_32x32x16_bf16 v[80:95], v[232:235], v[124:127], v[80:95]
	v_add_f32_e32 v224, v144, v224
	v_add_f32_e32 v225, v162, v225
	v_exp_f32_e32 v212, v152
	v_mfma_f32_32x32x16_bf16 v[64:79], v[236:239], v[124:127], v[64:79]
	v_add_f32_e32 v226, v160, v226
	v_exp_f32_e32 v213, v153
	v_add_f32_e32 v227, v161, v227
	ds_read_b128 v[232:235], v249 offset:49280
	ds_read_b128 v[236:239], v249 offset:61568
	s_waitcnt lgkmcnt(4)
	v_mfma_f32_32x32x16_bf16 v[80:95], v[200:203], v[120:123], v[80:95]
	v_add_f32_e32 v224, v163, v224
	v_exp_f32_e32 v215, v151
	v_add_f32_e32 v225, v175, v225
	v_mfma_f32_32x32x16_bf16 v[64:79], v[204:207], v[120:123], v[64:79]
	v_add_f32_e32 v226, v212, v226
	v_add_f32_e32 v227, v213, v227
	v_exp_f32_e32 v228, v158
	ds_read_b128 v[200:203], v246 offset:49408
	ds_read_b128 v[204:207], v246 offset:61696
	s_waitcnt lgkmcnt(4)
	v_mfma_f32_32x32x16_bf16 v[80:95], v[216:219], v[116:119], v[80:95]
	v_add_f32_e32 v224, v214, v224
	v_exp_f32_e32 v229, v159
	v_add_f32_e32 v225, v215, v225
	v_mfma_f32_32x32x16_bf16 v[64:79], v[220:223], v[116:119], v[64:79]
	v_exp_f32_e32 v230, v154
	v_add_f32_e32 v226, v164, v226
	v_exp_f32_e32 v231, v155
	ds_read_b128 v[216:219], v247 offset:49408
	ds_read_b128 v[220:223], v247 offset:61696
	s_waitcnt lgkmcnt(4)
	v_mfma_f32_32x32x16_bf16 v[80:95], v[232:235], v[112:115], v[80:95]
	v_add_f32_e32 v227, v165, v227
	v_add_f32_e32 v224, v228, v224
	v_add_f32_e32 v225, v229, v225
	v_mfma_f32_32x32x16_bf16 v[64:79], v[236:239], v[112:115], v[64:79]
	v_add_f32_e32 v226, v230, v226
	v_add_f32_e32 v227, v231, v227
	v_add_f32_e32 v224, v224, v225
	v_add_f32_e32 v226, v226, v227
	v_add_f32_e32 v173, v224, v226
	v_mov_b32_e32 v174, v173
	s_nop 1
	ds_read_b128 v[232:235], v248 offset:49408
	ds_read_b128 v[236:239], v248 offset:61696
	s_waitcnt lgkmcnt(4)
	v_mfma_f32_32x32x16_bf16 v[80:95], v[200:203], v[108:111], v[80:95]
	v_permlane32_swap_b32_e32 v173, v174
	v_cvt_pk_bf16_f32 v150, v185, v189
	v_cvt_pk_bf16_f32 v151, v186, v190
	v_mfma_f32_32x32x16_bf16 v[64:79], v[204:207], v[108:111], v[64:79]
	v_cvt_pk_bf16_f32 v152, v187, v191
	v_cvt_pk_bf16_f32 v153, v184, v188
	v_cvt_pk_bf16_f32 v154, v178, v182
	ds_read_b128 v[200:203], v249 offset:49408
	ds_read_b128 v[204:207], v249 offset:61696
	s_waitcnt lgkmcnt(4)
	v_mfma_f32_32x32x16_bf16 v[80:95], v[216:219], v[104:107], v[80:95]
	v_cvt_pk_bf16_f32 v155, v179, v183
	v_cvt_pk_bf16_f32 v156, v176, v180
	v_cvt_pk_bf16_f32 v157, v177, v181
	v_mfma_f32_32x32x16_bf16 v[64:79], v[220:223], v[104:107], v[64:79]
	v_cvt_pk_bf16_f32 v158, v144, v162
	v_cvt_pk_bf16_f32 v159, v160, v161
	v_cvt_pk_bf16_f32 v160, v163, v175
	s_waitcnt lgkmcnt(2)
	v_mfma_f32_32x32x16_bf16 v[80:95], v[232:235], v[100:103], v[80:95]
	v_cvt_pk_bf16_f32 v161, v212, v213
	v_cvt_pk_bf16_f32 v162, v214, v215
	v_cvt_pk_bf16_f32 v163, v164, v165
	v_mfma_f32_32x32x16_bf16 v[64:79], v[236:239], v[100:103], v[64:79]
	v_cvt_pk_bf16_f32 v164, v228, v229
	v_cvt_pk_bf16_f32 v165, v230, v231
	v_permlane32_swap_b32_e32 v150, v152
	s_waitcnt lgkmcnt(0)
	v_mfma_f32_32x32x16_bf16 v[80:95], v[200:203], v[96:99], v[80:95]
	v_permlane32_swap_b32_e32 v151, v153
	v_permlane32_swap_b32_e32 v154, v156
	v_permlane32_swap_b32_e32 v155, v157
	v_mfma_f32_32x32x16_bf16 v[64:79], v[204:207], v[96:99], v[64:79]
	v_permlane32_swap_b32_e32 v158, v160
	v_permlane32_swap_b32_e32 v159, v161
	v_permlane32_swap_b32_e32 v162, v164
	v_permlane32_swap_b32_e32 v163, v165
	s_cmp_lg_u32 0, -1
	s_cselect_b32 s4, 0, 0
	s_add_i32 s40, s36, s4
	v_add_u32_e32 v144, s40, v250
	ds_read_b64_tr_b16 v[176:177], v144 offset:0
	ds_read_b64_tr_b16 v[178:179], v144 offset:0x800
	ds_read_b64_tr_b16 v[180:181], v144 offset:0x1000
	ds_read_b64_tr_b16 v[182:183], v144 offset:0x1800
	ds_read_b64_tr_b16 v[184:185], v144 offset:0x2000
	ds_read_b64_tr_b16 v[186:187], v144 offset:0x2800
	ds_read_b64_tr_b16 v[188:189], v144 offset:0x3000
	ds_read_b64_tr_b16 v[190:191], v144 offset:0x3800
	s_waitcnt lgkmcnt(0)
	s_nop 0
	v_mfma_f32_32x32x16_bf16 v[0:15], v[150:153], v[176:179], v[0:15]
	ds_read_b64_tr_b16 v[176:177], v144 offset:0x200
	ds_read_b64_tr_b16 v[178:179], v144 offset:0xa00
	v_mfma_f32_32x32x16_bf16 v[0:15], v[154:157], v[180:183], v[0:15]
	ds_read_b64_tr_b16 v[180:181], v144 offset:0x1200
	ds_read_b64_tr_b16 v[182:183], v144 offset:0x1a00
	v_mfma_f32_32x32x16_bf16 v[0:15], v[158:161], v[184:187], v[0:15]
	ds_read_b64_tr_b16 v[184:185], v144 offset:0x2200
	ds_read_b64_tr_b16 v[186:187], v144 offset:0x2a00
	ds_read_b64_tr_b16 v[192:193], v144 offset:0x3200
	ds_read_b64_tr_b16 v[194:195], v144 offset:0x3a00
	s_waitcnt lgkmcnt(0)
	v_mfma_f32_32x32x16_bf16 v[0:15], v[162:165], v[188:191], v[0:15]
	v_mfma_f32_32x32x16_bf16 v[48:63], v[150:153], v[176:179], v[48:63]
	ds_read_b64_tr_b16 v[176:177], v144 offset:0x400
	ds_read_b64_tr_b16 v[178:179], v144 offset:0xc00
	v_mfma_f32_32x32x16_bf16 v[48:63], v[154:157], v[180:183], v[48:63]
	ds_read_b64_tr_b16 v[180:181], v144 offset:0x1400
	ds_read_b64_tr_b16 v[182:183], v144 offset:0x1c00
	v_mfma_f32_32x32x16_bf16 v[48:63], v[158:161], v[184:187], v[48:63]
	ds_read_b64_tr_b16 v[184:185], v144 offset:0x2400
	ds_read_b64_tr_b16 v[186:187], v144 offset:0x2c00
	ds_read_b64_tr_b16 v[188:189], v144 offset:0x3400
	ds_read_b64_tr_b16 v[190:191], v144 offset:0x3c00
	s_waitcnt lgkmcnt(0)
	v_mfma_f32_32x32x16_bf16 v[48:63], v[162:165], v[192:195], v[48:63]
	v_mfma_f32_32x32x16_bf16 v[32:47], v[150:153], v[176:179], v[32:47]
	ds_read_b64_tr_b16 v[176:177], v144 offset:0x600
	ds_read_b64_tr_b16 v[178:179], v144 offset:0xe00
	v_mfma_f32_32x32x16_bf16 v[32:47], v[154:157], v[180:183], v[32:47]
	ds_read_b64_tr_b16 v[180:181], v144 offset:0x1600
	ds_read_b64_tr_b16 v[182:183], v144 offset:0x1e00
	v_mfma_f32_32x32x16_bf16 v[32:47], v[158:161], v[184:187], v[32:47]
	ds_read_b64_tr_b16 v[184:185], v144 offset:0x2600
	ds_read_b64_tr_b16 v[186:187], v144 offset:0x2e00
	ds_read_b64_tr_b16 v[192:193], v144 offset:0x3600
	ds_read_b64_tr_b16 v[194:195], v144 offset:0x3e00
	s_waitcnt lgkmcnt(0)
	v_mfma_f32_32x32x16_bf16 v[32:47], v[162:165], v[188:191], v[32:47]
	v_mfma_f32_32x32x16_bf16 v[16:31], v[150:153], v[176:179], v[16:31]
	v_max_f32_e32 v144, v80, v81
	v_max3_f32 v144, v144, v82, v83
	v_max3_f32 v144, v144, v84, v85
	v_max3_f32 v144, v144, v86, v87
	v_max3_f32 v144, v144, v88, v89
	v_max3_f32 v144, v144, v90, v91
	v_mfma_f32_32x32x16_bf16 v[16:31], v[154:157], v[180:183], v[16:31]
	v_max3_f32 v144, v144, v92, v93
	v_max3_f32 v144, v144, v94, v95
	v_max3_f32 v144, v144, v64, v65
	v_max3_f32 v144, v144, v66, v67
	v_max3_f32 v144, v144, v68, v69
	v_max3_f32 v144, v144, v70, v71
	v_max3_f32 v144, v144, v72, v73
	v_max3_f32 v144, v144, v74, v75
	v_mfma_f32_32x32x16_bf16 v[16:31], v[158:161], v[184:187], v[16:31]
	v_max3_f32 v144, v144, v76, v77
	v_max3_f32 v144, v144, v78, v79
	v_mov_b32_e32 v150, v144
	s_nop 1
	v_permlane32_swap_b32_e32 v144, v150
	v_max_f32_e32 v144, v144, v150
	v_sub_f32_e32 v150, v144, v172
	v_max_f32_e32 v144, v172, v144
	v_mfma_f32_32x32x16_bf16 v[16:31], v[162:165], v[192:195], v[16:31]
	v_sub_f32_e32 v151, v172, v144
	v_mul_f32_e32 v151, 0x3dd53b94, v151
	v_exp_f32_e32 v151, v151
	v_cmp_ge_f32_e32 vcc, s63, v150
	s_cmp_eq_u64 vcc, exec
	s_cselect_b64 s[4:5], -1, 0
	s_waitcnt vmcnt(0)
	v_cndmask_b32_e64 v175, v151, 1.0, s[4:5]
	v_cmp_gt_f32_e32 vcc, 1.0, v175
	s_waitcnt vmcnt(0)
	s_barrier
	s_cbranch_vccz .LBB0_1102
	s_and_saveexec_b64 s[36:37], s[2:3]
	ds_write_b32 v149, v175 offset:128
	s_or_b64 exec, exec, s[36:37]
	s_waitcnt lgkmcnt(0)
	v_add_u32_e32 v162, v147, v148
	ds_read_b128 v[150:153], v162 offset:224
	ds_read_b128 v[154:157], v162 offset:192
	ds_read_b128 v[158:161], v162 offset:160
	ds_read_b128 v[162:165], v162 offset:128
	s_waitcnt lgkmcnt(3)
	v_pk_mul_f32 v[12:13], v[12:13], v[150:151]
	s_waitcnt lgkmcnt(2)
	v_pk_mul_f32 v[8:9], v[8:9], v[154:155]
	s_waitcnt lgkmcnt(1)
	v_pk_mul_f32 v[4:5], v[4:5], v[158:159]
	v_pk_mul_f32 v[14:15], v[14:15], v[152:153]
	v_pk_mul_f32 v[10:11], v[10:11], v[156:157]
	v_pk_mul_f32 v[6:7], v[6:7], v[160:161]
	s_waitcnt lgkmcnt(0)
	v_pk_mul_f32 v[2:3], v[2:3], v[164:165]
	v_pk_mul_f32 v[0:1], v[0:1], v[162:163]
	v_pk_mul_f32 v[60:61], v[60:61], v[150:151]
	v_pk_mul_f32 v[56:57], v[56:57], v[154:155]
	v_pk_mul_f32 v[52:53], v[52:53], v[158:159]
	v_pk_mul_f32 v[62:63], v[62:63], v[152:153]
	v_pk_mul_f32 v[58:59], v[58:59], v[156:157]
	v_pk_mul_f32 v[54:55], v[54:55], v[160:161]
	v_pk_mul_f32 v[50:51], v[50:51], v[164:165]
	v_pk_mul_f32 v[48:49], v[48:49], v[162:163]
	v_pk_mul_f32 v[44:45], v[44:45], v[150:151]
	v_pk_mul_f32 v[40:41], v[40:41], v[154:155]
	v_pk_mul_f32 v[36:37], v[36:37], v[158:159]
	v_pk_mul_f32 v[46:47], v[46:47], v[152:153]
	v_pk_mul_f32 v[42:43], v[42:43], v[156:157]
	v_pk_mul_f32 v[38:39], v[38:39], v[160:161]
	v_pk_mul_f32 v[34:35], v[34:35], v[164:165]
	v_pk_mul_f32 v[32:33], v[32:33], v[162:163]
	v_pk_mul_f32 v[28:29], v[28:29], v[150:151]
	v_pk_mul_f32 v[24:25], v[24:25], v[154:155]
	v_pk_mul_f32 v[20:21], v[20:21], v[158:159]
	v_pk_mul_f32 v[30:31], v[30:31], v[152:153]
	v_pk_mul_f32 v[26:27], v[26:27], v[156:157]
	v_pk_mul_f32 v[22:23], v[22:23], v[160:161]
	v_pk_mul_f32 v[18:19], v[18:19], v[164:165]
	v_pk_mul_f32 v[16:17], v[16:17], v[162:163]
.LBB0_1102:
	v_cndmask_b32_e64 v150, v144, v172, s[4:5]
	v_mul_f32_e32 v176, 0xbdd53b94, v150
	v_fmamk_f32 v187, v66, 0x3dd53b94, v176
	v_fmamk_f32 v185, v64, 0x3dd53b94, v176
	v_fmamk_f32 v186, v65, 0x3dd53b94, v176
	v_fmamk_f32 v188, v67, 0x3dd53b94, v176
	s_cmp_lg_u32 0, -1
	s_cselect_b32 s4, 0, 0
	s_add_i32 s5, s4, s0
	s_add_i32 m0, s5, 0x12000
	v_fmamk_f32 v178, v69, 0x3dd53b94, v176
	s_add_u32 s98, s34, s24
	s_addc_u32 s99, s35, s25
	global_load_lds_dwordx4 v240, s[98:99]
	s_add_i32 m0, s5, 0x14000
	v_fmamk_f32 v179, v70, 0x3dd53b94, v176
	global_load_lds_dwordx4 v241, s[98:99]
	s_add_i32 m0, s5, 0x16000
	v_fmamk_f32 v189, v68, 0x3dd53b94, v176
	global_load_lds_dwordx4 v242, s[98:99]
	v_fmamk_f32 v180, v71, 0x3dd53b94, v176
	s_add_i32 s5, s1, s46
	s_mov_b32 m0, s5
	v_fmamk_f32 v94, v94, 0x3dd53b94, v176
	s_add_u32 s100, s38, s26
	s_addc_u32 s101, s39, s27
	global_load_lds_dwordx4 v243, s[100:101]
	s_add_i32 m0, s5, 0x2000
	v_exp_f32_e32 v151, v94
	global_load_lds_dwordx4 v244, s[100:101]
	v_fmamk_f32 v80, v80, 0x3dd53b94, v176
	v_fmamk_f32 v81, v81, 0x3dd53b94, v176
	v_fmamk_f32 v82, v82, 0x3dd53b94, v176
	v_fmamk_f32 v83, v83, 0x3dd53b94, v176
	v_fmamk_f32 v84, v84, 0x3dd53b94, v176
	v_fmamk_f32 v85, v85, 0x3dd53b94, v176
	v_fmamk_f32 v86, v86, 0x3dd53b94, v176
	v_fmamk_f32 v87, v87, 0x3dd53b94, v176
	v_fmamk_f32 v88, v88, 0x3dd53b94, v176
	v_fmamk_f32 v89, v89, 0x3dd53b94, v176
	v_fmamk_f32 v90, v90, 0x3dd53b94, v176
	v_fmamk_f32 v91, v91, 0x3dd53b94, v176
	v_fmamk_f32 v92, v92, 0x3dd53b94, v176
	v_fmamk_f32 v93, v93, 0x3dd53b94, v176
	v_fmamk_f32 v95, v95, 0x3dd53b94, v176
	v_fmamk_f32 v181, v72, 0x3dd53b94, v176
	v_fmamk_f32 v182, v73, 0x3dd53b94, v176
	v_fmamk_f32 v183, v74, 0x3dd53b94, v176
	v_fmamk_f32 v184, v75, 0x3dd53b94, v176
	v_fmamk_f32 v177, v76, 0x3dd53b94, v176
	v_exp_f32_e32 v164, v80
	v_exp_f32_e32 v172, v81
	v_exp_f32_e32 v162, v82
	v_exp_f32_e32 v165, v83
	v_exp_f32_e32 v161, v84
	v_exp_f32_e32 v163, v85
	v_exp_f32_e32 v159, v86
	v_exp_f32_e32 v160, v87
	v_exp_f32_e32 v156, v88
	v_exp_f32_e32 v158, v89
	v_exp_f32_e32 v155, v90
	v_exp_f32_e32 v157, v91
	v_exp_f32_e32 v152, v92
	v_exp_f32_e32 v154, v93
	v_exp_f32_e32 v153, v95
	v_fmamk_f32 v190, v77, 0x3dd53b94, v176
	v_fmamk_f32 v191, v78, 0x3dd53b94, v176
	v_fmac_f32_e32 v176, 0x3dd53b94, v79
	ds_read_b128 v[64:67], v246 offset:24576
	ds_read_b128 v[68:71], v246 offset:36864
	ds_read_b128 v[232:235], v247 offset:24576
	ds_read_b128 v[236:239], v247 offset:36864
	ds_read_b128 v[200:203], v248 offset:24576
	ds_read_b128 v[204:207], v248 offset:36864
	s_waitcnt lgkmcnt(4)
	v_mfma_f32_32x32x16_bf16 v[80:95], v[64:67], v[140:143], 0
	v_exp_f32_e32 v180, v180
	v_exp_f32_e32 v181, v181
	v_exp_f32_e32 v182, v182
	v_mfma_f32_32x32x16_bf16 v[64:79], v[68:71], v[140:143], 0
	v_exp_f32_e32 v183, v183
	v_exp_f32_e32 v184, v184
	v_exp_f32_e32 v190, v190
	ds_read_b128 v[216:219], v249 offset:24576
	ds_read_b128 v[220:223], v249 offset:36864
	s_waitcnt lgkmcnt(4)
	v_mfma_f32_32x32x16_bf16 v[80:95], v[232:235], v[136:139], v[80:95]
	v_exp_f32_e32 v191, v191
	v_exp_f32_e32 v144, v185
	v_exp_f32_e32 v185, v186
	v_mfma_f32_32x32x16_bf16 v[64:79], v[236:239], v[136:139], v[64:79]
	v_exp_f32_e32 v186, v187
	v_exp_f32_e32 v187, v188
	v_exp_f32_e32 v188, v189
	ds_read_b128 v[232:235], v246 offset:24704
	ds_read_b128 v[236:239], v246 offset:36992
	s_waitcnt lgkmcnt(4)
	v_mfma_f32_32x32x16_bf16 v[80:95], v[200:203], v[132:135], v[80:95]
	v_exp_f32_e32 v189, v178
	v_exp_f32_e32 v214, v176
	v_mfma_f32_32x32x16_bf16 v[64:79], v[204:207], v[132:135], v[64:79]
	ds_read_b128 v[200:203], v247 offset:24704
	ds_read_b128 v[204:207], v247 offset:36992
	s_waitcnt lgkmcnt(4)
	v_mfma_f32_32x32x16_bf16 v[80:95], v[216:219], v[128:131], v[80:95]
	v_add_f32_e32 v224, v164, v161
	v_add_f32_e32 v225, v172, v163
	v_add_f32_e32 v226, v162, v159
	v_mfma_f32_32x32x16_bf16 v[64:79], v[220:223], v[128:131], v[64:79]
	v_add_f32_e32 v227, v165, v160
	v_add_f32_e32 v224, v156, v224
	v_add_f32_e32 v225, v158, v225
	v_add_f32_e32 v226, v155, v226
	ds_read_b128 v[216:219], v248 offset:24704
	ds_read_b128 v[220:223], v248 offset:36992
	s_waitcnt lgkmcnt(4)
	v_mfma_f32_32x32x16_bf16 v[80:95], v[232:235], v[124:127], v[80:95]
	v_add_f32_e32 v227, v157, v227
	v_add_f32_e32 v224, v152, v224
	v_add_f32_e32 v225, v154, v225
	v_mfma_f32_32x32x16_bf16 v[64:79], v[236:239], v[124:127], v[64:79]
	v_add_f32_e32 v226, v151, v226
	v_add_f32_e32 v227, v153, v227
	v_add_f32_e32 v224, v144, v224
	ds_read_b128 v[232:235], v249 offset:24704
	ds_read_b128 v[236:239], v249 offset:36992
	s_waitcnt lgkmcnt(4)
	v_mfma_f32_32x32x16_bf16 v[80:95], v[200:203], v[120:123], v[80:95]
	v_add_f32_e32 v225, v185, v225
	v_exp_f32_e32 v212, v179
	v_add_f32_e32 v226, v186, v226
	v_mfma_f32_32x32x16_bf16 v[64:79], v[204:207], v[120:123], v[64:79]
	v_add_f32_e32 v227, v187, v227
	v_add_f32_e32 v224, v188, v224
	v_add_f32_e32 v225, v189, v225
	ds_read_b128 v[200:203], v246 offset:24832
	ds_read_b128 v[204:207], v246 offset:37120
	s_waitcnt lgkmcnt(4)
	v_mfma_f32_32x32x16_bf16 v[80:95], v[216:219], v[116:119], v[80:95]
	v_add_f32_e32 v226, v212, v226
	v_add_f32_e32 v227, v180, v227
	v_exp_f32_e32 v213, v177
	v_mfma_f32_32x32x16_bf16 v[64:79], v[220:223], v[116:119], v[64:79]
	v_add_f32_e32 v224, v181, v224
	v_add_f32_e32 v225, v182, v225
	v_add_f32_e32 v226, v183, v226
	ds_read_b128 v[216:219], v247 offset:24832
	ds_read_b128 v[220:223], v247 offset:37120
	s_waitcnt lgkmcnt(4)
	v_mfma_f32_32x32x16_bf16 v[80:95], v[232:235], v[112:115], v[80:95]
	v_add_f32_e32 v227, v184, v227
	v_add_f32_e32 v224, v213, v224
	v_add_f32_e32 v225, v190, v225
	v_mfma_f32_32x32x16_bf16 v[64:79], v[236:239], v[112:115], v[64:79]
	v_add_f32_e32 v226, v191, v226
	v_add_f32_e32 v227, v214, v227
	v_add_f32_e32 v224, v224, v225
	v_add_f32_e32 v226, v226, v227
	v_add_f32_e32 v192, v224, v226
	v_mov_b32_e32 v193, v192
	s_nop 1
	ds_read_b128 v[232:235], v248 offset:24832
	ds_read_b128 v[236:239], v248 offset:37120
	s_waitcnt lgkmcnt(4)
	v_mfma_f32_32x32x16_bf16 v[80:95], v[200:203], v[108:111], v[80:95]
	v_permlane32_swap_b32_e32 v192, v193
	v_cvt_pk_bf16_f32 v176, v164, v172
	v_cvt_pk_bf16_f32 v177, v162, v165
	v_mfma_f32_32x32x16_bf16 v[64:79], v[204:207], v[108:111], v[64:79]
	v_cvt_pk_bf16_f32 v178, v161, v163
	v_cvt_pk_bf16_f32 v179, v159, v160
	v_cvt_pk_bf16_f32 v156, v156, v158
	ds_read_b128 v[200:203], v249 offset:24832
	ds_read_b128 v[204:207], v249 offset:37120
	s_waitcnt lgkmcnt(4)
	v_mfma_f32_32x32x16_bf16 v[80:95], v[216:219], v[104:107], v[80:95]
	v_cvt_pk_bf16_f32 v157, v155, v157
	v_cvt_pk_bf16_f32 v158, v152, v154
	v_cvt_pk_bf16_f32 v159, v151, v153
	v_mfma_f32_32x32x16_bf16 v[64:79], v[220:223], v[104:107], v[64:79]
	v_cvt_pk_bf16_f32 v152, v144, v185
	v_cvt_pk_bf16_f32 v153, v186, v187
	v_cvt_pk_bf16_f32 v154, v188, v189
	s_waitcnt lgkmcnt(2)
	v_mfma_f32_32x32x16_bf16 v[80:95], v[232:235], v[100:103], v[80:95]
	v_cvt_pk_bf16_f32 v155, v212, v180
	v_cvt_pk_bf16_f32 v160, v181, v182
	v_cvt_pk_bf16_f32 v161, v183, v184
	v_mfma_f32_32x32x16_bf16 v[64:79], v[236:239], v[100:103], v[64:79]
	v_cvt_pk_bf16_f32 v162, v213, v190
	v_cvt_pk_bf16_f32 v163, v191, v214
	v_permlane32_swap_b32_e32 v176, v178
	s_waitcnt lgkmcnt(0)
	v_mfma_f32_32x32x16_bf16 v[80:95], v[200:203], v[96:99], v[80:95]
	v_permlane32_swap_b32_e32 v177, v179
	v_permlane32_swap_b32_e32 v156, v158
	v_permlane32_swap_b32_e32 v157, v159
	v_mfma_f32_32x32x16_bf16 v[64:79], v[204:207], v[96:99], v[64:79]
	v_permlane32_swap_b32_e32 v152, v154
	v_permlane32_swap_b32_e32 v153, v155
	v_permlane32_swap_b32_e32 v160, v162
	v_permlane32_swap_b32_e32 v161, v163
	s_add_i32 s4, s48, s4
	v_add_u32_e32 v144, s4, v250
	ds_read_b64_tr_b16 v[180:181], v144 offset:0
	ds_read_b64_tr_b16 v[182:183], v144 offset:0x800
	ds_read_b64_tr_b16 v[184:185], v144 offset:0x1000
	ds_read_b64_tr_b16 v[186:187], v144 offset:0x1800
	ds_read_b64_tr_b16 v[188:189], v144 offset:0x2000
	ds_read_b64_tr_b16 v[190:191], v144 offset:0x2800
	ds_read_b64_tr_b16 v[194:195], v144 offset:0x3000
	ds_read_b64_tr_b16 v[196:197], v144 offset:0x3800
	s_waitcnt lgkmcnt(0)
	s_nop 0
	v_mfma_f32_32x32x16_bf16 v[0:15], v[176:179], v[180:183], v[0:15]
	ds_read_b64_tr_b16 v[180:181], v144 offset:0x200
	ds_read_b64_tr_b16 v[182:183], v144 offset:0xa00
	v_mfma_f32_32x32x16_bf16 v[0:15], v[156:159], v[184:187], v[0:15]
	ds_read_b64_tr_b16 v[184:185], v144 offset:0x1200
	ds_read_b64_tr_b16 v[186:187], v144 offset:0x1a00
	v_mfma_f32_32x32x16_bf16 v[0:15], v[152:155], v[188:191], v[0:15]
	ds_read_b64_tr_b16 v[188:189], v144 offset:0x2200
	ds_read_b64_tr_b16 v[190:191], v144 offset:0x2a00
	ds_read_b64_tr_b16 v[198:199], v144 offset:0x3200
	ds_read_b64_tr_b16 v[200:201], v144 offset:0x3a00
	s_waitcnt lgkmcnt(0)
	v_mfma_f32_32x32x16_bf16 v[0:15], v[160:163], v[194:197], v[0:15]
	v_mfma_f32_32x32x16_bf16 v[48:63], v[176:179], v[180:183], v[48:63]
	ds_read_b64_tr_b16 v[180:181], v144 offset:0x400
	ds_read_b64_tr_b16 v[182:183], v144 offset:0xc00
	v_mfma_f32_32x32x16_bf16 v[48:63], v[156:159], v[184:187], v[48:63]
	ds_read_b64_tr_b16 v[184:185], v144 offset:0x1400
	ds_read_b64_tr_b16 v[186:187], v144 offset:0x1c00
	v_mfma_f32_32x32x16_bf16 v[48:63], v[152:155], v[188:191], v[48:63]
	ds_read_b64_tr_b16 v[188:189], v144 offset:0x2400
	ds_read_b64_tr_b16 v[190:191], v144 offset:0x2c00
	ds_read_b64_tr_b16 v[194:195], v144 offset:0x3400
	ds_read_b64_tr_b16 v[196:197], v144 offset:0x3c00
	s_waitcnt lgkmcnt(0)
	v_mfma_f32_32x32x16_bf16 v[48:63], v[160:163], v[198:201], v[48:63]
	v_mfma_f32_32x32x16_bf16 v[32:47], v[176:179], v[180:183], v[32:47]
	ds_read_b64_tr_b16 v[180:181], v144 offset:0x600
	ds_read_b64_tr_b16 v[182:183], v144 offset:0xe00
	v_mfma_f32_32x32x16_bf16 v[32:47], v[156:159], v[184:187], v[32:47]
	ds_read_b64_tr_b16 v[184:185], v144 offset:0x1600
	ds_read_b64_tr_b16 v[186:187], v144 offset:0x1e00
	v_mfma_f32_32x32x16_bf16 v[32:47], v[152:155], v[188:191], v[32:47]
	ds_read_b64_tr_b16 v[188:189], v144 offset:0x2600
	ds_read_b64_tr_b16 v[190:191], v144 offset:0x2e00
	ds_read_b64_tr_b16 v[198:199], v144 offset:0x3600
	ds_read_b64_tr_b16 v[200:201], v144 offset:0x3e00
	s_waitcnt lgkmcnt(0)
	v_mfma_f32_32x32x16_bf16 v[32:47], v[160:163], v[194:197], v[32:47]
	v_mfma_f32_32x32x16_bf16 v[16:31], v[176:179], v[180:183], v[16:31]
	v_max_f32_e32 v144, v80, v81
	v_max3_f32 v144, v144, v82, v83
	v_max3_f32 v144, v144, v84, v85
	v_max3_f32 v144, v144, v86, v87
	v_max3_f32 v144, v144, v88, v89
	v_max3_f32 v144, v144, v90, v91
	v_mfma_f32_32x32x16_bf16 v[16:31], v[156:159], v[184:187], v[16:31]
	v_max3_f32 v144, v144, v92, v93
	v_max3_f32 v144, v144, v94, v95
	v_max3_f32 v144, v144, v64, v65
	v_max3_f32 v144, v144, v66, v67
	v_max3_f32 v144, v144, v68, v69
	v_max3_f32 v144, v144, v70, v71
	v_max3_f32 v144, v144, v72, v73
	v_max3_f32 v144, v144, v74, v75
	v_mfma_f32_32x32x16_bf16 v[16:31], v[152:155], v[188:191], v[16:31]
	v_max3_f32 v144, v144, v76, v77
	v_max3_f32 v144, v144, v78, v79
	v_mov_b32_e32 v151, v144
	s_nop 1
	v_permlane32_swap_b32_e32 v144, v151
	v_max_f32_e32 v144, v144, v151
	v_max_f32_e32 v151, v150, v144
	v_sub_f32_e32 v152, v144, v150
	v_mfma_f32_32x32x16_bf16 v[16:31], v[160:163], v[198:201], v[16:31]
	v_sub_f32_e32 v144, v150, v151
	v_mul_f32_e32 v144, 0x3dd53b94, v144
	v_exp_f32_e32 v144, v144
	v_cmp_ge_f32_e32 vcc, s63, v152
	s_cmp_eq_u64 vcc, exec
	s_cselect_b64 s[4:5], -1, 0
	s_waitcnt vmcnt(0)
	v_cndmask_b32_e64 v144, v144, 1.0, s[4:5]
	v_cmp_gt_f32_e32 vcc, 1.0, v144
	s_waitcnt vmcnt(0)
	s_barrier
	s_cbranch_vccz .LBB0_1106
	s_and_saveexec_b64 s[34:35], s[2:3]
	ds_write_b32 v149, v144 offset:128
	s_or_b64 exec, exec, s[34:35]
	s_waitcnt lgkmcnt(0)
	v_add_u32_e32 v164, v147, v148
	ds_read_b128 v[152:155], v164 offset:224
	ds_read_b128 v[156:159], v164 offset:192
	ds_read_b128 v[160:163], v164 offset:160
	ds_read_b128 v[176:179], v164 offset:128
	s_waitcnt lgkmcnt(3)
	v_pk_mul_f32 v[12:13], v[12:13], v[152:153]
	s_waitcnt lgkmcnt(2)
	v_pk_mul_f32 v[8:9], v[8:9], v[156:157]
	s_waitcnt lgkmcnt(1)
	v_pk_mul_f32 v[4:5], v[4:5], v[160:161]
	v_pk_mul_f32 v[14:15], v[14:15], v[154:155]
	v_pk_mul_f32 v[10:11], v[10:11], v[158:159]
	v_pk_mul_f32 v[6:7], v[6:7], v[162:163]
	s_waitcnt lgkmcnt(0)
	v_pk_mul_f32 v[2:3], v[2:3], v[178:179]
	v_pk_mul_f32 v[0:1], v[0:1], v[176:177]
	v_pk_mul_f32 v[60:61], v[60:61], v[152:153]
	v_pk_mul_f32 v[56:57], v[56:57], v[156:157]
	v_pk_mul_f32 v[52:53], v[52:53], v[160:161]
	v_pk_mul_f32 v[62:63], v[62:63], v[154:155]
	v_pk_mul_f32 v[58:59], v[58:59], v[158:159]
	v_pk_mul_f32 v[54:55], v[54:55], v[162:163]
	v_pk_mul_f32 v[50:51], v[50:51], v[178:179]
	v_pk_mul_f32 v[48:49], v[48:49], v[176:177]
	v_pk_mul_f32 v[44:45], v[44:45], v[152:153]
	v_pk_mul_f32 v[40:41], v[40:41], v[156:157]
	v_pk_mul_f32 v[36:37], v[36:37], v[160:161]
	v_pk_mul_f32 v[46:47], v[46:47], v[154:155]
	v_pk_mul_f32 v[42:43], v[42:43], v[158:159]
	v_pk_mul_f32 v[38:39], v[38:39], v[162:163]
	v_pk_mul_f32 v[34:35], v[34:35], v[178:179]
	v_pk_mul_f32 v[32:33], v[32:33], v[176:177]
	v_pk_mul_f32 v[28:29], v[28:29], v[152:153]
	v_pk_mul_f32 v[24:25], v[24:25], v[156:157]
	v_pk_mul_f32 v[20:21], v[20:21], v[160:161]
	v_pk_mul_f32 v[30:31], v[30:31], v[154:155]
	v_pk_mul_f32 v[26:27], v[26:27], v[158:159]
	v_pk_mul_f32 v[22:23], v[22:23], v[162:163]
	v_pk_mul_f32 v[18:19], v[18:19], v[178:179]
	v_pk_mul_f32 v[16:17], v[16:17], v[176:177]
